# S5 second pass: y stored straight from the MFMA result layout (four 2-byte stores per lane), LDS transpose and its two round trips removed
# speedup vs baseline: 1.0071x; 1.0011x over previous
; #define LAS __attribute__((address_space(3)))
; #define LDS_WAIT() asm volatile("s_waitcnt lgkmcnt(0)" ::: "memory")
; #define MFMA16(a, b, c) __builtin_amdgcn_mfma_f32_16x16x32_bf16(a, b, c, 0, 0, 0)
; __device__ __forceinline__ bf16_t tobf(float x) { return (bf16_t)pk2(x, 0.f); }
; __device__ __forceinline__ void s5_phase(LAS unsigned char* lds, const bf16_t* USSM, const float* S5A, const float* S5B, const float* c_re, const float* c_im, const float* dskip,
;                                          bf16_t* YSSM, int tid, int lane, int wave) {
;     ...
;         for (int tb = 0; tb < 64; ++tb) {
;             bf16x8 a = *(const bf16x8*)(ub + (size_t)(tb * 16 + r16) * 1024 + (q4 & 1) * 8); *(LAS bf16x8*)(UST + r16 * 16 + (q4 & 1) * 8) = a; if (q4 >= 2) a = zf;
; #pragma unroll
;             for (int nt = 0; nt < 8; ++nt) { const f32x4 acc = MFMA16(a, bfr[nt], z4);
; #pragma unroll
;                 for (int i = 0; i < 4; ++i) BU[(q4 * 4 + i) * 132 + nt * 16 + r16] = acc[i]; }
;             LDS_WAIT();
; #pragma unroll
;             for (int t = 0; t < 16; ++t) { const float br = BU[t * 132 + lane], bi = BU[t * 132 + 64 + lane];
;                 const float nr = are * xr - aim * xi + br, ni = are * xi + aim * xr + bi; xr = nr; xi = ni;
;                 XB[t * 136 + lane] = tobf(xr); XB[t * 136 + 64 + lane] = tobf(xi); }
;             LDS_WAIT();
.LBB0_595:
	s_lshl_b32 s6, s6, 1
	v_add_u32_e32 v82, s14, v116
	v_lshl_add_u64 v[100:101], v[84:85], 0, s[6:7]
	s_mov_b32 s6, 0
	v_lshlrev_b32_e32 v152, 1, v81
	v_and_b32_e32 v153, 3, v81
	v_lshlrev_b32_e32 v153, 3, v153
	v_sub_u32_e32 v152, v152, v153
	v_lshrrev_b32_e32 v153, 2, v81
	v_lshlrev_b32_e32 v153, 11, v153
	v_sub_u32_e32 v152, v152, v153
	v_add_u32_e32 v168, 0x1000, v152
	v_ashrrev_i32_e32 v153, 31, v152
	v_ashrrev_i32_e32 v169, 31, v168
	global_load_dwordx4 v[148:151], v[96:97], off
	v_lshl_add_u64 v[96:97], v[96:97], 0, s[56:57]
	s_waitcnt vmcnt(0)
.LBB0_596:
	v_mov_b32_e32 v158, v76
	v_mov_b32_e32 v159, v77
	v_add_u32_e32 v141, v115, v112
	v_add_u32_e32 v146, s6, v82
	v_add_u32_e32 v104, 0x1000, v141
	v_ashrrev_i32_e32 v147, 31, v146
	s_add_i32 s6, s6, 16
	s_cmpk_eq_i32 s6, 0x400
	s_waitcnt vmcnt(4)
	v_cndmask_b32_e64 v55, v151, 0, s[4:5]
	v_cndmask_b32_e64 v54, v150, 0, s[4:5]
	v_cndmask_b32_e64 v53, v149, 0, s[4:5]
	v_cndmask_b32_e64 v52, v148, 0, s[4:5]
	ds_write_b128 v109, v[148:151] offset:16896
	global_load_dwordx4 v[148:151], v[96:97], off
	v_lshl_add_u64 v[96:97], v[96:97], 0, s[56:57]
	s_nop 0
	v_mfma_f32_16x16x32_bf16 v[56:59], v[52:55], v[0:3], 0
	v_mfma_f32_16x16x32_bf16 v[60:63], v[52:55], v[4:7], 0
	v_mfma_f32_16x16x32_bf16 v[64:67], v[52:55], v[8:11], 0
	v_mfma_f32_16x16x32_bf16 v[68:71], v[52:55], v[16:19], 0
	v_mfma_f32_16x16x32_bf16 v[72:75], v[52:55], v[12:15], 0
	v_mfma_f32_16x16x32_bf16 v[76:79], v[52:55], v[20:23], 0
	v_mfma_f32_16x16x32_bf16 v[142:145], v[52:55], v[24:27], 0
	v_mfma_f32_16x16x32_bf16 v[48:51], v[52:55], v[28:31], 0
	s_nop 1
	ds_write2_b32 v124, v56, v60 offset1:16
	ds_write2_b32 v124, v57, v61 offset0:132 offset1:148
	ds_write2_b32 v125, v58, v62 offset0:8 offset1:24
	ds_write2_b32 v125, v59, v63 offset0:140 offset1:156
	ds_write2_b32 v124, v64, v68 offset0:32 offset1:48
	ds_write2_b32 v124, v65, v69 offset0:164 offset1:180
	ds_write2_b32 v125, v66, v70 offset0:40 offset1:56
	ds_write2_b32 v125, v67, v71 offset0:172 offset1:188
	ds_write2_b32 v124, v72, v76 offset0:64 offset1:80
	ds_write2_b32 v124, v73, v77 offset0:196 offset1:212
	ds_write2_b32 v125, v74, v78 offset0:72 offset1:88
	ds_write2_b32 v125, v75, v79 offset0:204 offset1:220
	ds_write2_b32 v124, v142, v48 offset0:96 offset1:112
	ds_write2_b32 v124, v143, v49 offset0:228 offset1:244
	ds_write2_b32 v125, v144, v50 offset0:104 offset1:120
	ds_write2_b32 v125, v145, v51 offset0:236 offset1:252
	s_waitcnt lgkmcnt(0)
	ds_read2st64_b32 v[222:223], v111 offset0:16 offset1:17
	ds_read2st64_b32 v[224:225], v126 offset0:18 offset1:19
	ds_read2st64_b32 v[226:227], v127 offset0:20 offset1:21
	ds_read2st64_b32 v[228:229], v128 offset0:22 offset1:23
	s_waitcnt lgkmcnt(3)
	v_fma_f32 v160, v94, v158, v222
	v_fma_f32 v161, v94, v159, v223
	v_fma_f32 v162, -v95, v159, v160
	v_fma_f32 v163, v95, v158, v161
	ds_read2st64_b32 v[230:231], v129 offset0:24 offset1:25
	v_cvt_pk_bf16_f32 v164, v162, v83
	v_cvt_pk_bf16_f32 v165, v163, v83
	ds_write_b16 v118, v164 offset:12544
	ds_write_b16 v118, v165 offset:12672
	s_waitcnt lgkmcnt(5)
	v_fma_f32 v160, v94, v162, v224
	v_fma_f32 v161, v94, v163, v225
	v_fma_f32 v158, -v95, v163, v160
	v_fma_f32 v159, v95, v162, v161
	ds_read2st64_b32 v[232:233], v130 offset0:26 offset1:27
	v_cvt_pk_bf16_f32 v166, v158, v83
	v_cvt_pk_bf16_f32 v167, v159, v83
	ds_write_b16 v118, v166 offset:12816
	ds_write_b16 v118, v167 offset:12944
	s_waitcnt lgkmcnt(7)
	v_fma_f32 v160, v94, v158, v226
	v_fma_f32 v161, v94, v159, v227
	v_fma_f32 v162, -v95, v159, v160
	v_fma_f32 v163, v95, v158, v161
	ds_read2st64_b32 v[234:235], v131 offset0:28 offset1:29
	v_cvt_pk_bf16_f32 v164, v162, v83
	v_cvt_pk_bf16_f32 v165, v163, v83
	ds_write_b16 v118, v164 offset:13088
	ds_write_b16 v118, v165 offset:13216
	s_waitcnt lgkmcnt(9)
	v_fma_f32 v160, v94, v162, v228
	v_fma_f32 v161, v94, v163, v229
	v_fma_f32 v158, -v95, v163, v160
	v_fma_f32 v159, v95, v162, v161
	ds_read2st64_b32 v[236:237], v132 offset0:30 offset1:31
	v_cvt_pk_bf16_f32 v166, v158, v83
	v_cvt_pk_bf16_f32 v167, v159, v83
	ds_write_b16 v118, v166 offset:13360
	ds_write_b16 v118, v167 offset:13488
	s_waitcnt lgkmcnt(11)
	v_fma_f32 v160, v94, v158, v230
	v_fma_f32 v161, v94, v159, v231
	v_fma_f32 v162, -v95, v159, v160
	v_fma_f32 v163, v95, v158, v161
	ds_read2st64_b32 v[238:239], v133 offset0:32 offset1:33
	v_cvt_pk_bf16_f32 v164, v162, v83
	v_cvt_pk_bf16_f32 v165, v163, v83
	ds_write_b16 v118, v164 offset:13632
	ds_write_b16 v118, v165 offset:13760
	s_waitcnt lgkmcnt(11)
	v_fma_f32 v160, v94, v162, v232
	v_fma_f32 v161, v94, v163, v233
	v_fma_f32 v158, -v95, v163, v160
	v_fma_f32 v159, v95, v162, v161
	ds_read2st64_b32 v[240:241], v134 offset0:34 offset1:35
	v_cvt_pk_bf16_f32 v166, v158, v83
	v_cvt_pk_bf16_f32 v167, v159, v83
	ds_write_b16 v118, v166 offset:13904
	ds_write_b16 v118, v167 offset:14032
	s_waitcnt lgkmcnt(11)
	v_fma_f32 v160, v94, v158, v234
	v_fma_f32 v161, v94, v159, v235
	v_fma_f32 v162, -v95, v159, v160
	v_fma_f32 v163, v95, v158, v161
	ds_read2st64_b32 v[242:243], v135 offset0:36 offset1:37
	v_cvt_pk_bf16_f32 v164, v162, v83
	v_cvt_pk_bf16_f32 v165, v163, v83
	ds_write_b16 v118, v164 offset:14176
	ds_write_b16 v118, v165 offset:14304
	s_waitcnt lgkmcnt(11)
	v_fma_f32 v160, v94, v162, v236
	v_fma_f32 v161, v94, v163, v237
	v_fma_f32 v158, -v95, v163, v160
	v_fma_f32 v159, v95, v162, v161
	ds_read2st64_b32 v[244:245], v136 offset0:38 offset1:39
	v_cvt_pk_bf16_f32 v166, v158, v83
	v_cvt_pk_bf16_f32 v167, v159, v83
	ds_write_b16 v118, v166 offset:14448
	ds_write_b16 v118, v167 offset:14576
	s_waitcnt lgkmcnt(11)
; #define LAS __attribute__((address_space(3)))
; __device__ __forceinline__ unsigned pk2(float lo, float hi) { unsigned r; asm volatile("v_cvt_pk_bf16_f32 %0, %1, %2" : "=v"(r) : "v"(lo), "v"(hi)); return r; }
; __device__ __forceinline__ float gelu_tanh(float x) { return x * sigm(1.5957691216f * (x + 0.044715f * x * x * x)); }
; #define LDS_WAIT() asm volatile("s_waitcnt lgkmcnt(0)" ::: "memory")
; #define MFMA16(a, b, c) __builtin_amdgcn_mfma_f32_16x16x32_bf16(a, b, c, 0, 0, 0)
; __device__ __forceinline__ bf16_t tobf(float x) { return (bf16_t)pk2(x, 0.f); }
; __device__ __forceinline__ void s5_phase(LAS unsigned char* lds, const bf16_t* USSM, const float* S5A, const float* S5B, const float* c_re, const float* c_im, const float* dskip,
;                                          bf16_t* YSSM, int tid, int lane, int wave) {
;     ...
;                 XB[t * 136 + lane] = tobf(xr); XB[t * 136 + 64 + lane] = tobf(xi); }
;             LDS_WAIT();
;             f32x4 y = z4;
; #pragma unroll
;             for (int ks = 0; ks < 4; ++ks) y = MFMA16(*(const LAS bf16x8*)(XB + r16 * 136 + ks * 32 + q4 * 8), cfr[ks], y);
; #pragma unroll
;             for (int i = 0; i < 4; ++i) { const float u = bflo((unsigned)UST[(q4 * 4 + i) * 16 + r16]); BU[(q4 * 4 + i) * 16 + r16] = gelu_tanh(y[i] + dsk * u); }
;             LDS_WAIT();
;             { const f32x4 v = *(const LAS f32x4*)(BU + (lane >> 2) * 16 + (lane & 3) * 4); u32x2 o; o.x = pk2(v[0], v[1]); o.y = pk2(v[2], v[3]);
;               *(u32x2*)(YSSM + ((size_t)(b * SEQ + wave * 1024 + tb * 16 + (lane >> 2))) * 1024 + g * 16 + (lane & 3) * 4) = o; }
;             LDS_WAIT();
	v_fma_f32 v160, v94, v158, v238
	v_fma_f32 v161, v94, v159, v239
	v_fma_f32 v162, -v95, v159, v160
	v_fma_f32 v163, v95, v158, v161
	ds_read2st64_b32 v[246:247], v137 offset0:40 offset1:41
	v_cvt_pk_bf16_f32 v164, v162, v83
	v_cvt_pk_bf16_f32 v165, v163, v83
	ds_write_b16 v118, v164 offset:14720
	ds_write_b16 v118, v165 offset:14848
	s_waitcnt lgkmcnt(11)
	v_fma_f32 v160, v94, v162, v240
	v_fma_f32 v161, v94, v163, v241
	v_fma_f32 v158, -v95, v163, v160
	v_fma_f32 v159, v95, v162, v161
	ds_read2st64_b32 v[248:249], v138 offset0:42 offset1:43
	v_cvt_pk_bf16_f32 v166, v158, v83
	v_cvt_pk_bf16_f32 v167, v159, v83
	ds_write_b16 v118, v166 offset:14992
	ds_write_b16 v118, v167 offset:15120
	s_waitcnt lgkmcnt(11)
	v_fma_f32 v160, v94, v158, v242
	v_fma_f32 v161, v94, v159, v243
	v_fma_f32 v162, -v95, v159, v160
	v_fma_f32 v163, v95, v158, v161
	ds_read2st64_b32 v[250:251], v139 offset0:44 offset1:45
	v_cvt_pk_bf16_f32 v164, v162, v83
	v_cvt_pk_bf16_f32 v165, v163, v83
	ds_write_b16 v118, v164 offset:15264
	ds_write_b16 v118, v165 offset:15392
	s_waitcnt lgkmcnt(11)
	v_fma_f32 v160, v94, v162, v244
	v_fma_f32 v161, v94, v163, v245
	v_fma_f32 v158, -v95, v163, v160
	v_fma_f32 v159, v95, v162, v161
	ds_read2st64_b32 v[252:253], v140 offset0:46 offset1:47
	v_cvt_pk_bf16_f32 v166, v158, v83
	v_cvt_pk_bf16_f32 v167, v159, v83
	ds_write_b16 v118, v166 offset:15536
	ds_write_b16 v118, v167 offset:15664
	s_waitcnt lgkmcnt(11)
	v_fma_f32 v160, v94, v158, v246
	v_fma_f32 v161, v94, v159, v247
	v_fma_f32 v162, -v95, v159, v160
	v_fma_f32 v163, v95, v158, v161
	v_cvt_pk_bf16_f32 v164, v162, v83
	v_cvt_pk_bf16_f32 v165, v163, v83
	ds_write_b16 v118, v164 offset:15808
	ds_write_b16 v118, v165 offset:15936
	s_waitcnt lgkmcnt(10)
	v_fma_f32 v160, v94, v162, v248
	v_fma_f32 v161, v94, v163, v249
	v_fma_f32 v158, -v95, v163, v160
	v_fma_f32 v159, v95, v162, v161
	v_cvt_pk_bf16_f32 v166, v158, v83
	v_cvt_pk_bf16_f32 v167, v159, v83
	ds_write_b16 v118, v166 offset:16080
	ds_write_b16 v118, v167 offset:16208
	s_waitcnt lgkmcnt(9)
	v_fma_f32 v160, v94, v158, v250
	v_fma_f32 v161, v94, v159, v251
	v_fma_f32 v162, -v95, v159, v160
	v_fma_f32 v163, v95, v158, v161
	v_cvt_pk_bf16_f32 v164, v162, v83
	v_cvt_pk_bf16_f32 v165, v163, v83
	ds_write_b16 v118, v164 offset:16352
	ds_write_b16 v118, v165 offset:16480
	s_waitcnt lgkmcnt(8)
	v_fma_f32 v160, v94, v162, v252
	v_fma_f32 v161, v94, v163, v253
	v_fma_f32 v76, -v95, v163, v160
	v_fma_f32 v77, v95, v162, v161
	v_cvt_pk_bf16_f32 v166, v76, v83
	v_cvt_pk_bf16_f32 v167, v77, v83
	ds_write_b16 v118, v166 offset:16624
	ds_write_b16 v118, v167 offset:16752
	s_waitcnt lgkmcnt(0)
	ds_read_b128 v[48:51], v119 offset:12544
	ds_read_b128 v[52:55], v119 offset:12608
	ds_read_b128 v[56:59], v119 offset:12672
	s_waitcnt lgkmcnt(2)
	v_mfma_f32_16x16x32_bf16 v[48:51], v[48:51], v[32:35], 0
	ds_read_b128 v[60:63], v119 offset:12736
	ds_read_u16 v64, v113 offset:16896
	ds_read_u16 v65, v115 offset:16928
	s_waitcnt lgkmcnt(4)
	v_mfma_f32_16x16x32_bf16 v[48:51], v[52:55], v[36:39], v[48:51]
	ds_read_u16 v52, v115 offset:16960
	ds_read_u16 v53, v115 offset:16992
	s_waitcnt lgkmcnt(3)
	v_lshlrev_b32_e32 v54, 16, v64
	s_waitcnt lgkmcnt(2)
	v_lshlrev_b32_e32 v55, 16, v65
	v_mfma_f32_16x16x32_bf16 v[48:51], v[56:59], v[40:43], v[48:51]
	s_waitcnt lgkmcnt(1)
	v_lshlrev_b32_e32 v52, 16, v52
	s_waitcnt lgkmcnt(0)
	v_lshlrev_b32_e32 v53, 16, v53
	v_mfma_f32_16x16x32_bf16 v[48:51], v[60:63], v[44:47], v[48:51]
	s_nop 7
	v_fma_f32 v48, v123, v54, v48
	v_fma_f32 v49, v123, v55, v49
	v_fma_f32 v50, v123, v52, v50
	v_fmac_f32_e32 v51, v123, v53
	v_mul_f32_e32 v52, 0x3d372713, v48
	v_mul_f32_e32 v53, 0x3d372713, v49
	v_mul_f32_e32 v54, 0x3d372713, v50
	v_mul_f32_e32 v55, 0x3d372713, v51
	v_mul_f32_e32 v52, v48, v52
	v_mul_f32_e32 v53, v49, v53
	v_mul_f32_e32 v54, v50, v54
	v_mul_f32_e32 v55, v51, v55
	v_fma_f32 v52, v48, v52, v48
	v_fma_f32 v53, v49, v53, v49
	v_fma_f32 v54, v50, v54, v50
	v_fma_f32 v55, v51, v55, v51
	v_mul_f32_e32 v52, 0x3fcc422a, v52
	v_mul_f32_e32 v53, 0x3fcc422a, v53
	v_mul_f32_e32 v54, 0x3fcc422a, v54
	v_mul_f32_e32 v55, 0x3fcc422a, v55
	v_mul_f32_e32 v52, 0xbfb8aa3b, v52
	v_mul_f32_e32 v53, 0xbfb8aa3b, v53
	v_mul_f32_e32 v54, 0xbfb8aa3b, v54
	v_mul_f32_e32 v55, 0xbfb8aa3b, v55
	v_exp_f32_e32 v52, v52
	v_exp_f32_e32 v53, v53
	v_exp_f32_e32 v54, v54
	v_exp_f32_e32 v55, v55
	v_add_f32_e32 v52, 1.0, v52
	v_add_f32_e32 v53, 1.0, v53
	v_add_f32_e32 v54, 1.0, v54
	v_add_f32_e32 v55, 1.0, v55
	v_rcp_f32_e32 v52, v52
	v_rcp_f32_e32 v53, v53
	v_rcp_f32_e32 v54, v54
	v_rcp_f32_e32 v55, v55
	v_mul_f32_e32 v48, v48, v52
	v_mul_f32_e32 v49, v49, v53
	v_mul_f32_e32 v50, v50, v54
	v_mul_f32_e32 v51, v51, v55
	v_lshlrev_b64 v[52:53], 11, v[146:147]
	v_lshl_add_u64 v[52:53], v[100:101], 0, v[52:53]
	v_lshl_add_u64 v[54:55], v[52:53], 0, v[168:169]
	v_lshl_add_u64 v[52:53], v[52:53], 0, v[152:153]
	v_cvt_pk_bf16_f32 v48, v48, v48
	v_cvt_pk_bf16_f32 v49, v49, v49
	v_cvt_pk_bf16_f32 v50, v50, v50
	v_cvt_pk_bf16_f32 v51, v51, v51
	global_store_short v[52:53], v48, off
	global_store_short v[52:53], v49, off offset:2048
	global_store_short v[54:55], v50, off
	global_store_short v[54:55], v51, off offset:2048
	s_waitcnt lgkmcnt(0)
	s_cbranch_scc0 .LBB0_596
	s_add_i32 s43, s43, s84
	s_add_i32 s27, s27, s33
	s_add_i32 s42, s42, s84
	s_cmpk_gt_i32 s43, 0xff
	s_cbranch_scc0 .LBB0_568
